# HGRN2 scan: one static s_setprio 1 for the gate waves (the younger half of each scan workgroup), reset after the scan
# speedup vs baseline: 1.0070x; 1.0041x over previous
; __device__ __forceinline__ float bflo(unsigned u) { return __uint_as_float(u << 16); }
; __device__ __forceinline__ float bfhi(unsigned u) { return __uint_as_float(u & 0xffff0000u); }
; #define LAS __attribute__((address_space(3)))
; DI void hg_load_gate(const HgGate& c, int g, unsigned (&xo_)[8], unsigned (&q_)[8]) {
;     const int sg_ = g >= 8; const int r0_ = HG_T0D(g, c.dir) + 8 * c.tqs; const bf16* xb_ = sg_ ? c.x1u : c.x0u; const size_t xp_ = sg_ ? U1W : UC1W;
; #pragma unroll
;     for (int i = 0; i < 8; ++i) { xo_[i] = ((const unsigned*)(xb_ + (size_t)(r0_ + i) * xp_))[c.kp]; q_[i] = ((const unsigned*)(c.q1u + (size_t)(r0_ + i) * U1W))[c.kp]; }
; }
; DI void hg_sums(const HgGate& c, int par, const unsigned (&xo_)[8]) {
;     float a0_ = 0.f, a1_ = 0.f;
; #pragma unroll
;     for (int i = 0; i < 8; ++i) { a0_ += pg8::bflo(xo_[i]); a1_ += pg8::bfhi(xo_[i]); }
;     *(LAS f32x2_t*)(c.GT + ((par & 1) * 4 + c.tqs) * 128 + 2 * c.kp) = (f32x2_t){a0_, a1_};
; }
; DI void hgrn_item(int item, const float* lbl, const bf16* U1, const bf16* UC1, const bf16* VT, const bf16* VTC, bf16* OF, bf16* OB, LAS unsigned char* lds) {
;     ...
;     if (gate_role) {
;         const HgGate gc{dir, tqs, kp, x1u, x0u, q1u, GT, lds};
;         hg_load_gate(gc, 0, xo_c, q_c); hg_load_gate(gc, 1, xo_n, q_n);
;         hg_sums(gc, 0, xo_c);
;         asm volatile("s_waitcnt lgkmcnt(0)\n\ts_barrier" ::: "memory");
.LBB0_471:
	s_setprio 1
	s_ashr_i32 s9, s8, 31
	s_lshl_b64 s[8:9], s[8:9], 14
	s_add_u32 s0, s72, s8
	s_addc_u32 s24, s73, s9
	s_lshl_b64 s[8:9], s[96:97], 12
	v_readlane_b32 s26, v249, 31
	v_readlane_b32 s27, v249, 32
	s_add_u32 s8, s26, s8
	s_addc_u32 s9, s27, s9
	s_lshl_b32 s20, s20, 11
	s_add_u32 s8, s8, s20
	s_addc_u32 s9, s9, 0
	s_lshl_b32 s21, s21, 1
	s_add_u32 s40, s8, s21
	s_addc_u32 s41, s9, 0
	s_add_u32 s8, s0, s20
	s_addc_u32 s9, s24, 0
	s_add_u32 s8, s8, s21
	s_addc_u32 s9, s9, 0
	s_add_u32 s42, s8, 0x800
	s_addc_u32 s43, s9, 0
	s_add_u32 s8, s0, s21
	s_addc_u32 s9, s24, 0
	s_and_b64 s[20:21], s[22:23], exec
	s_cselect_b32 s21, 0, 0xe0
	s_lshl_b32 s20, s19, 3
	s_or_b32 s21, s20, s21
	s_lshl_b32 s24, s21, 12
	s_add_u32 s24, s40, s24
	s_addc_u32 s25, s41, 0
	v_lshlrev_b32_e32 v192, 2, v186
	global_load_dword v50, v192, s[24:25]
	s_lshl_b32 s24, s21, 14
	s_add_u32 s24, s8, s24
	s_addc_u32 s25, s9, 0
	s_or_b32 s26, s21, 1
	global_load_dword v44, v192, s[24:25]
	s_lshl_b32 s24, s26, 12
	s_add_u32 s24, s40, s24
	s_addc_u32 s25, s41, 0
	global_load_dword v53, v192, s[24:25]
	s_lshl_b32 s24, s26, 14
	s_add_u32 s24, s8, s24
	s_addc_u32 s25, s9, 0
	s_or_b32 s26, s21, 2
	global_load_dword v45, v192, s[24:25]
	s_lshl_b32 s24, s26, 12
	s_add_u32 s24, s40, s24
	s_addc_u32 s25, s41, 0
	global_load_dword v57, v192, s[24:25]
	s_lshl_b32 s24, s26, 14
	s_add_u32 s24, s8, s24
	s_addc_u32 s25, s9, 0
	s_or_b32 s26, s21, 3
	global_load_dword v46, v192, s[24:25]
	s_lshl_b32 s24, s26, 12
	s_add_u32 s24, s40, s24
	s_addc_u32 s25, s41, 0
	global_load_dword v59, v192, s[24:25]
	s_lshl_b32 s24, s26, 14
	s_add_u32 s24, s8, s24
	s_addc_u32 s25, s9, 0
	s_or_b32 s26, s21, 4
	global_load_dword v47, v192, s[24:25]
	s_lshl_b32 s24, s26, 12
	s_add_u32 s24, s40, s24
	s_addc_u32 s25, s41, 0
	global_load_dword v63, v192, s[24:25]
	s_lshl_b32 s24, s26, 14
	s_add_u32 s24, s8, s24
	s_addc_u32 s25, s9, 0
	s_or_b32 s26, s21, 5
	global_load_dword v48, v192, s[24:25]
	s_lshl_b32 s24, s26, 12
	s_add_u32 s24, s40, s24
	s_addc_u32 s25, s41, 0
	global_load_dword v64, v192, s[24:25]
	s_lshl_b32 s24, s26, 14
	s_add_u32 s24, s8, s24
	s_addc_u32 s25, s9, 0
	s_or_b32 s26, s21, 6
	global_load_dword v49, v192, s[24:25]
	s_lshl_b32 s24, s26, 12
	s_add_u32 s24, s40, s24
	s_addc_u32 s25, s41, 0
	global_load_dword v66, v192, s[24:25]
	s_lshl_b32 s24, s26, 14
	s_add_u32 s24, s8, s24
	s_addc_u32 s25, s9, 0
	s_or_b32 s21, s21, 7
	global_load_dword v51, v192, s[24:25]
	s_lshl_b32 s24, s21, 12
	s_add_u32 s24, s40, s24
	s_addc_u32 s25, s41, 0
	s_lshl_b32 s21, s21, 14
	global_load_dword v67, v192, s[24:25]
	s_add_u32 s24, s8, s21
	s_addc_u32 s25, s9, 0
	global_load_dword v56, v192, s[24:25]
	s_and_b64 s[24:25], s[22:23], exec
	s_cselect_b32 s21, 32, 0xc0
	s_or_b32 s21, s20, s21
	s_lshl_b32 s24, s21, 12
	s_add_u32 s24, s40, s24
	s_addc_u32 s25, s41, 0
	global_load_dword v82, v192, s[24:25]
	s_lshl_b32 s24, s21, 14
	s_add_u32 s24, s8, s24
	s_addc_u32 s25, s9, 0
	s_or_b32 s26, s21, 1
	global_load_dword v52, v192, s[24:25]
	s_lshl_b32 s24, s26, 12
	s_add_u32 s24, s40, s24
	s_addc_u32 s25, s41, 0
	global_load_dword v83, v192, s[24:25]
	s_lshl_b32 s24, s26, 14
	s_add_u32 s24, s8, s24
	s_addc_u32 s25, s9, 0
	s_or_b32 s26, s21, 2
	global_load_dword v54, v192, s[24:25]
	s_lshl_b32 s24, s26, 12
	s_add_u32 s24, s40, s24
	s_addc_u32 s25, s41, 0
	global_load_dword v84, v192, s[24:25]
	s_lshl_b32 s24, s26, 14
	s_add_u32 s24, s8, s24
	s_addc_u32 s25, s9, 0
	s_or_b32 s26, s21, 3
	global_load_dword v55, v192, s[24:25]
	s_lshl_b32 s24, s26, 12
	s_add_u32 s24, s40, s24
	s_addc_u32 s25, s41, 0
	global_load_dword v85, v192, s[24:25]
	s_lshl_b32 s24, s26, 14
	s_add_u32 s24, s8, s24
	s_addc_u32 s25, s9, 0
	s_or_b32 s26, s21, 4
	global_load_dword v58, v192, s[24:25]
	s_lshl_b32 s24, s26, 12
	s_add_u32 s24, s40, s24
	s_addc_u32 s25, s41, 0
	global_load_dword v86, v192, s[24:25]
	s_lshl_b32 s24, s26, 14
	s_add_u32 s24, s8, s24
	s_addc_u32 s25, s9, 0
	s_or_b32 s26, s21, 5
	global_load_dword v60, v192, s[24:25]
	s_lshl_b32 s24, s26, 12
	s_add_u32 s24, s40, s24
	s_addc_u32 s25, s41, 0
	global_load_dword v87, v192, s[24:25]
	s_lshl_b32 s24, s26, 14
	s_add_u32 s24, s8, s24
	s_addc_u32 s25, s9, 0
	s_or_b32 s26, s21, 6
	global_load_dword v61, v192, s[24:25]
	s_lshl_b32 s24, s26, 12
	s_add_u32 s24, s40, s24
	s_addc_u32 s25, s41, 0
	global_load_dword v88, v192, s[24:25]
	s_lshl_b32 s24, s26, 14
	s_add_u32 s24, s8, s24
	s_addc_u32 s25, s9, 0
	s_or_b32 s21, s21, 7
	global_load_dword v62, v192, s[24:25]
	s_lshl_b32 s24, s21, 12
	s_add_u32 s24, s40, s24
	s_addc_u32 s25, s41, 0
	s_lshl_b32 s21, s21, 14
	global_load_dword v89, v192, s[24:25]
	s_add_u32 s24, s8, s21
	s_addc_u32 s25, s9, 0
	global_load_dword v65, v192, s[24:25]
	s_waitcnt vmcnt(0) lgkmcnt(0)
	v_lshlrev_b32_e32 v2, 16, v50
	v_and_b32_e32 v3, 0xffff0000, v50
	v_pk_add_f32 v[2:3], v[2:3], 0 op_sel_hi:[1,0]
	v_lshlrev_b32_e32 v4, 16, v53
	v_and_b32_e32 v5, 0xffff0000, v53
	v_pk_add_f32 v[2:3], v[2:3], v[4:5]
	v_lshlrev_b32_e32 v4, 16, v57
	v_and_b32_e32 v5, 0xffff0000, v57
	v_pk_add_f32 v[2:3], v[2:3], v[4:5]
	v_lshlrev_b32_e32 v4, 16, v59
	v_and_b32_e32 v5, 0xffff0000, v59
	v_pk_add_f32 v[2:3], v[2:3], v[4:5]
	v_lshlrev_b32_e32 v4, 16, v63
	v_and_b32_e32 v5, 0xffff0000, v63
	v_pk_add_f32 v[2:3], v[2:3], v[4:5]
	v_lshlrev_b32_e32 v4, 16, v64
	v_and_b32_e32 v5, 0xffff0000, v64
	v_pk_add_f32 v[2:3], v[2:3], v[4:5]
	v_lshlrev_b32_e32 v4, 16, v66
	v_and_b32_e32 v5, 0xffff0000, v66
	v_pk_add_f32 v[2:3], v[2:3], v[4:5]
	v_lshlrev_b32_e32 v4, 16, v67
	v_and_b32_e32 v5, 0xffff0000, v67
	v_pk_add_f32 v[2:3], v[2:3], v[4:5]
	v_lshl_add_u32 v4, s19, 9, v191
	s_cmp_eq_u32 s19, 0
	ds_write_b64 v4, v[2:3]
	s_cselect_b64 s[24:25], -1, 0
	s_cmp_eq_u32 s19, 3
	s_waitcnt lgkmcnt(0)
	s_barrier
	s_cselect_b64 s[26:27], -1, 0
	s_cmp_lt_u32 s19, 2
	s_cselect_b64 s[28:29], -1, 0
	s_cmp_gt_u32 s19, 1
	s_mov_b32 s0, 0
	v_lshl_add_u64 v[10:11], s[8:9], 0, v[192:193]
	s_mul_i32 s21, s19, 0x880
	s_mov_b32 s52, -3
	s_mov_b32 s33, 8
	s_movk_i32 s48, 0xff40
	s_movk_i32 s49, 0xa0
	s_cselect_b64 s[30:31], -1, 0
	s_branch .LBB0_474

;     __host__ __device__ void init2(int M, int N, int G_, int c_, int base_, int lim_) { init(M, N, G_, c_); base = base_; lim = lim_ < nwg ? lim_ : nwg; }
;     __host__ __device__ bool next(int i, Unit& u) const {
;         const long L = (long)base + (long)i * G + c; if (L >= lim) return false;
;         int wgid = (int)L; { const int q = nwg / NXCD, r = nwg % NXCD, xcd = wgid % NXCD, off = wgid / NXCD; wgid = (xcd < r ? xcd * (q + 1) : r * (q + 1) + (xcd - r) * q) + off; }
; __global__ void __launch_bounds__(512, 2) fwd_mega(Args args) {
;     ...
;                 pg8::StaticOrder S; S.init2(g.M, g.N, nh, bx, (G == 256) ? GU_SPLIT2 : GU_SPLIT, 1 << 30);
;                 pg8::gemm_phase<pg8::EpiStore, pg8::StaticOrder, true, true>(lds, g, S, E);
.LBB0_573:
	s_setprio 0
	v_readlane_b32 s0, v249, 43
	v_readlane_b32 s1, v249, 44
	v_readlane_b32 s66, v249, 9
	v_readlane_b32 s60, v249, 45
	v_readlane_b32 s62, v249, 29
	s_and_b64 vcc, exec, s[0:1]
	v_readlane_b32 s67, v249, 10
	v_readlane_b32 s61, v249, 46
	v_readlane_b32 s63, v249, 30
	s_cbranch_vccz .LBB0_599
	s_cmpk_eq_i32 s42, 0x100
	s_movk_i32 s0, 0x6b0
	s_cselect_b32 s0, s0, 0x6c0
	s_ashr_i32 s1, s2, 31
	s_add_u32 s4, s0, s2
	s_addc_u32 s5, 0, s1
	s_waitcnt lgkmcnt(0)
	v_mov_b64_e32 v[2:3], 0x7ff
	v_cmp_gt_i64_e32 vcc, s[4:5], v[2:3]
	v_readfirstlane_b32 s8, v1
	s_cbranch_vccnz .LBB0_599
	s_ashr_i32 s0, s4, 31
	s_lshr_b32 s0, s0, 29
	s_add_i32 s6, s4, s0
	s_and_b32 s0, s6, -8
	s_sub_i32 s3, s4, s0
	s_cmp_gt_i32 s3, -1
	s_cbranch_scc0 .LBB0_577
	s_lshl_b32 s9, s3, 8
	s_mov_b64 s[0:1], 0
	s_branch .LBB0_578
